# adds: QKV round-3 units rebalanced onto the workgroups with the shorter schedule
# speedup vs baseline: 1.0101x; 1.0101x over previous
; template <class Epi, class Sched, bool ALIGN_EPI = false, bool SP2 = false>
; __device__ __forceinline__ void gemm_phase(PG8_LAS unsigned char* lds, const Gemm g, const Sched& S, const Epi& E, const int wid_in) {
;     ...
;         const bool has_next = S.next(ui + 1, nxt);
;         const char* nA = has_next ? (const char*)g.A + (size_t)nxt.pm * tstep : cA; const char* nB = has_next ? (const char*)g.Bt + (size_t)nxt.pn * tstep : cB;
;     __host__ __device__ bool next(int i, Unit& u) const {
;         int L = i * G + c; if (L >= 384 + 512) return false;
;         if (L < 384) { u.pm = L / 3; u.pn = L - 3 * u.pm; } else { L -= 384; u.pm = 128 + (L >> 2); u.pn = 3 + (L & 3); }
;         return true;
.LBB0_261:
	s_add_i32 s74, s74, 1
	s_mul_i32 s2, s74, s30
	s_add_i32 s2, s2, s66
	s_cmp_eq_u32 s74, 3
	s_cselect_b32 s8, 0x80, 0
	s_cmp_eq_u32 s30, 0x100
	s_cselect_b32 s8, s8, 0
	s_xor_b32 s2, s2, s8
	s_cmpk_lt_i32 s2, 0x380
	s_cselect_b64 s[44:45], -1, 0
	s_cmpk_gt_i32 s2, 0x37f
	s_cbranch_scc1 .LBB0_266
	s_cmpk_gt_i32 s2, 0x17f
	s_mov_b64 s[46:47], -1
	s_cbranch_scc0 .LBB0_264
	s_add_i32 s8, s2, 0xfffffe80
	s_lshr_b32 s8, s8, 2
	s_add_i32 s38, s8, 0x80
	s_and_b32 s8, s2, 3
	s_add_i32 s42, s8, 3
	s_mov_b64 s[46:47], 0
